# plus: phase-3 items rebalanced (blocks with a long cross-chunk GLA scan skip the short items), redundant per-block L2 write-back at kernel entry removed
# speedup vs baseline: 1.2732x; 1.0065x over previous
; DEVINL int tidx() { int t = threadIdx.x; asm volatile("" : "+v"(t)); return t; }
; __global__ void __launch_bounds__(256, 2) mega_kernel(Params p) {
;     ...
;   XcdBarrier xb = xcd_barrier_post((unsigned*)(p.ws + OFF_BAR));
;   if (tidx() == 0) { __builtin_amdgcn_fence(__ATOMIC_RELEASE, ""); asm volatile("s_waitcnt vmcnt(0)" ::: "memory"); }
;   xcd_barrier(xb);
.LBB0_3:
	s_or_b64 exec, exec, s[2:3]
	v_mov_b32_e32 v1, v0
	s_nop 0
	v_cmp_eq_u32_e32 vcc, 0, v1
	s_and_saveexec_b64 s[2:3], vcc
	s_cbranch_execz .LBB0_5
	s_waitcnt vmcnt(0)
	s_waitcnt vmcnt(0)

; DEVINL void run_phase(const Params& p, char* smem, int ph) {
;     ...
;       for (int it = bid; it < S5CP_BLK + GLAB_ITEMS + S5CS_BLK; it += nb) {
;         if (it < S5CP_BLK) { __syncthreads(); s5_passC_prompt(p, smem, it); }
;         else if (it < S5CP_BLK + GLAB_ITEMS) gla_passB(p, it - S5CP_BLK);
;         else { __syncthreads(); s5_passC_sample(p, smem, it - S5CP_BLK - GLAB_ITEMS); }
;       }
.LBB0_452:
	s_or_b64 exec, exec, s[42:43]
	v_mov_b32_e32 v196, 0x180
	v_cmp_gt_i32_e32 vcc, 0x200, v79
	s_nop 1
	v_cndmask_b32_e32 v196, v196, v104, vcc
	v_subrev_u32_e32 v197, 0x200, v79
	v_cmp_gt_u32_e32 vcc, 0x80, v197
	v_mov_b32_e32 v197, 0x2000
	s_nop 0
	v_cndmask_b32_e32 v196, v196, v197, vcc
	v_cmp_ne_u32_e32 vcc, 0x200, v104
	s_nop 1
	v_cndmask_b32_e32 v196, v196, v104, vcc
	v_add_u32_e32 v79, v79, v196
	s_movk_i32 s0, 0xe7f
	v_cmp_lt_i32_e32 vcc, s0, v79
	v_lshlrev_b32_e32 v197, 5, v196
	v_add_u32_e32 v78, v78, v197
	s_or_b64 s[40:41], vcc, s[40:41]
	v_add_u16_e32 v75, v75, v196
	s_andn2_b64 exec, exec, s[40:41]
	s_cbranch_execz .LBB0_532
